# pool GEMM K-loop: eight extra LDS-DMA per wave per K-iter stream the X residual tile ahead of the 4-batch epilogue (waits vmcnt 8->12)
# baseline (speedup 1.0000x reference)
; #define PG8_STAGE(bufoff, gbase, voff) do { _Pragma("unroll") for (int _i = 0; _i < 2; ++_i) \
;         __builtin_amdgcn_global_load_lds((const unsigned*)((const char*)(gbase) + (voff)[_i]), (LAS unsigned*)(lds + (bufoff) + ldsw + _i * 8192), 16, 0, 0); } while (0)
; #define PG8_LDA(dst, b, h) do { _Pragma("unroll") for (int m = 0; m < 4; ++m) _Pragma("unroll") for (int k = 0; k < 2; ++k) dst[m][k] = *(const LAS bf16x8*)(lds + PG8_SA(b, h) + aoff + m * 2048 + k * 1024); } while (0)
; #define PG8_LDB(dst, b, h) do { _Pragma("unroll") for (int n = 0; n < 2; ++n) _Pragma("unroll") for (int k = 0; k < 2; ++k) dst[n][k] = *(const LAS bf16x8*)(lds + PG8_SB(b, h) + boff + n * 2048 + k * 1024); } while (0)
; #define PG8_MMA(ai, bj, At, Bt) do { __builtin_amdgcn_s_setprio(1); _Pragma("unroll") for (int m = 0; m < 4; ++m) _Pragma("unroll") for (int n = 0; n < 2; ++n) _Pragma("unroll") for (int k = 0; k < 2; ++k) \
;         acc[ai][bj][m][n] = __builtin_amdgcn_mfma_f32_16x16x32_bf16(Bt[n][k], At[m][k], acc[ai][bj][m][n], 0, 0, 0); __builtin_amdgcn_s_setprio(0); } while (0)
; #define PG8_WAIT_V(n) asm volatile("s_waitcnt vmcnt(" #n ")" ::: "memory")
; template <class Epi, bool ALIGN_EPI>
; __device__ __forceinline__ void gemm_phase(LAS unsigned char* lds, const Gemm g, int G, int cid, const Epi& E) {
;     ...
;     f32x4 acc[2][2][4][2];
; #pragma unroll
;     for (int a = 0; a < 2; ++a)
; #pragma unroll
;         for (int b = 0; b < 2; ++b)
; #pragma unroll
;             for (int m = 0; m < 4; ++m)
; #pragma unroll
;                 for (int n = 0; n < 2; ++n) acc[a][b][m][n] = (f32x4){0.f, 0.f, 0.f, 0.f};
;     ...
;         const bool has_next = S.next(ui + 1, nxt);
;         const char* nA = has_next ? tileA(g, nxt) : cA; const char* nB = has_next ? tileB(g, nxt) : cB;
;         for (int t = 0; t < nt; t += 2) {
;             const bool last = (t == nt - 2);
;             const char* a1 = cA + (size_t)(t + 1) * kA;
;             const char* a2 = last ? nA : cA + (size_t)(t + 2) * kA; const char* b2 = last ? nB : cB + (size_t)(t + 2) * kB;
;             const char* a3 = a2 + kA; const char* b3 = b2 + kB;
;             PG8_LDB(B0, 0, 0); PG8_LDB(B1, 0, 1); PG8_SCHED; PG8_LDA(At, 0, 0); PG8_STAGE(PG8_SA(1, 1), a1 + hA, voffA);
;             PG8_WAIT_V(8); PG8_WAIT_L(0); PG8_BAR; PG8_MMA(0, 0, At, B0); PG8_MMA(0, 1, At, B1); PG8_BAR; PG8_SCHED;
.LBB0_168:
	s_lshl_b64 s[6:7], s[48:49], 19
	s_add_u32 s6, s1, s6
	s_addc_u32 s7, s22, s7
	s_lshl_b32 s30, s74, 14
	s_and_b32 s30, s30, 0x4000
	s_add_u32 s48, s6, s30
	s_addc_u32 s49, s7, 0
	s_and_b64 s[6:7], s[44:45], exec
	s_cselect_b32 s30, s49, s53
	s_cselect_b32 s76, s48, s52
	s_add_u32 s77, s52, 0x20000
	v_mov_b32_e32 v0, 0
	s_addc_u32 s78, s53, 0
	s_mov_b32 s79, -2
	s_waitcnt lgkmcnt(0)
	v_mov_b32_e32 v1, v0
	v_mov_b32_e32 v2, v0
	v_mov_b32_e32 v3, v0
	v_mov_b32_e32 v4, v0
	v_mov_b32_e32 v5, v0
	v_mov_b32_e32 v6, v0
	v_mov_b32_e32 v7, v0
	v_mov_b32_e32 v16, v0
	v_mov_b32_e32 v17, v0
	v_mov_b32_e32 v18, v0
	v_mov_b32_e32 v19, v0
	v_mov_b32_e32 v20, v0
	v_mov_b32_e32 v21, v0
	v_mov_b32_e32 v22, v0
	v_mov_b32_e32 v23, v0
	v_mov_b32_e32 v32, v0
	v_mov_b32_e32 v33, v0
	v_mov_b32_e32 v34, v0
	v_mov_b32_e32 v35, v0
	v_mov_b32_e32 v36, v0
	v_mov_b32_e32 v37, v0
	v_mov_b32_e32 v38, v0
	v_mov_b32_e32 v39, v0
	v_mov_b32_e32 v48, v0
	v_mov_b32_e32 v49, v0
	v_mov_b32_e32 v50, v0
	v_mov_b32_e32 v51, v0
	v_mov_b32_e32 v52, v0
	v_mov_b32_e32 v53, v0
	v_mov_b32_e32 v54, v0
	v_mov_b32_e32 v55, v0
	v_mov_b32_e32 v8, v0
	v_mov_b32_e32 v9, v0
	v_mov_b32_e32 v10, v0
	v_mov_b32_e32 v11, v0
	v_mov_b32_e32 v12, v0
	v_mov_b32_e32 v13, v0
	v_mov_b32_e32 v14, v0
	v_mov_b32_e32 v15, v0
	v_mov_b32_e32 v24, v0
	v_mov_b32_e32 v25, v0
	v_mov_b32_e32 v26, v0
	v_mov_b32_e32 v27, v0
	v_mov_b32_e32 v28, v0
	v_mov_b32_e32 v29, v0
	v_mov_b32_e32 v30, v0
	v_mov_b32_e32 v31, v0
	v_mov_b32_e32 v40, v0
	v_mov_b32_e32 v41, v0
	v_mov_b32_e32 v42, v0
	v_mov_b32_e32 v43, v0
	v_mov_b32_e32 v44, v0
	v_mov_b32_e32 v45, v0
	v_mov_b32_e32 v46, v0
	v_mov_b32_e32 v47, v0
	v_mov_b32_e32 v56, v0
	v_mov_b32_e32 v57, v0
	v_mov_b32_e32 v58, v0
	v_mov_b32_e32 v59, v0
	v_mov_b32_e32 v60, v0
	v_mov_b32_e32 v61, v0
	v_mov_b32_e32 v62, v0
	v_mov_b32_e32 v63, v0
	v_mov_b32_e32 v64, v0
	v_mov_b32_e32 v65, v0
	v_mov_b32_e32 v66, v0
	v_mov_b32_e32 v67, v0
	v_mov_b32_e32 v72, v0
	v_mov_b32_e32 v73, v0
	v_mov_b32_e32 v74, v0
	v_mov_b32_e32 v75, v0
	v_mov_b32_e32 v112, v0
	v_mov_b32_e32 v113, v0
	v_mov_b32_e32 v114, v0
	v_mov_b32_e32 v115, v0
	v_mov_b32_e32 v116, v0
	v_mov_b32_e32 v117, v0
	v_mov_b32_e32 v118, v0
	v_mov_b32_e32 v119, v0
	v_mov_b32_e32 v128, v0
	v_mov_b32_e32 v129, v0
	v_mov_b32_e32 v130, v0
	v_mov_b32_e32 v131, v0
	v_mov_b32_e32 v132, v0
	v_mov_b32_e32 v133, v0
	v_mov_b32_e32 v134, v0
	v_mov_b32_e32 v135, v0
	v_mov_b32_e32 v148, v0
	v_mov_b32_e32 v149, v0
	v_mov_b32_e32 v150, v0
	v_mov_b32_e32 v151, v0
	v_mov_b32_e32 v152, v0
	v_mov_b32_e32 v153, v0
	v_mov_b32_e32 v154, v0
	v_mov_b32_e32 v155, v0
	v_mov_b32_e32 v104, v0
	v_mov_b32_e32 v105, v0
	v_mov_b32_e32 v106, v0
	v_mov_b32_e32 v107, v0
	v_mov_b32_e32 v108, v0
	v_mov_b32_e32 v109, v0
	v_mov_b32_e32 v110, v0
	v_mov_b32_e32 v111, v0
	v_mov_b32_e32 v120, v0
	v_mov_b32_e32 v121, v0
	v_mov_b32_e32 v122, v0
	v_mov_b32_e32 v123, v0
	v_mov_b32_e32 v124, v0
	v_mov_b32_e32 v125, v0
	v_mov_b32_e32 v126, v0
	v_mov_b32_e32 v127, v0
	v_mov_b32_e32 v140, v0
	v_mov_b32_e32 v141, v0
	v_mov_b32_e32 v142, v0
	v_mov_b32_e32 v143, v0
	v_mov_b32_e32 v144, v0
	v_mov_b32_e32 v145, v0
	v_mov_b32_e32 v146, v0
	v_mov_b32_e32 v147, v0
	v_mov_b32_e32 v156, v0
	v_mov_b32_e32 v157, v0
	v_mov_b32_e32 v158, v0
	v_mov_b32_e32 v159, v0
	v_mov_b32_e32 v160, v0
	v_mov_b32_e32 v161, v0
	v_mov_b32_e32 v162, v0
	v_mov_b32_e32 v163, v0
	v_mbcnt_lo_u32_b32 v224, -1, 0
	v_mbcnt_hi_u32_b32 v224, -1, v224
	v_lshlrev_b32_e32 v224, 4, v224
.LBB0_169:
	s_add_u32 s44, s50, 0x100
	s_addc_u32 s45, s51, 0
	s_add_i32 s6, 0, 0x10000
	s_cmp_eq_u32 s79, 4
	s_cselect_b32 s55, s43, s45
	s_cselect_b32 s54, s42, s44
	s_cselect_b32 s53, s30, s78
	s_cselect_b32 s52, s76, s77
	s_add_i32 s86, 0, 0x14000
	v_add_u32_e32 v84, s6, v212
	v_add_u32_e32 v100, s86, v212
	ds_read_b128 v[68:71], v84
	ds_read_b128 v[76:79], v84 offset:1024
	ds_read_b128 v[80:83], v84 offset:2048
	ds_read_b128 v[84:87], v84 offset:3072
	ds_read_b128 v[88:91], v100
	ds_read_b128 v[92:95], v100 offset:1024
	ds_read_b128 v[96:99], v100 offset:2048
	ds_read_b128 v[100:103], v100 offset:3072
	v_lshl_add_u64 v[198:199], s[50:51], 0, v[184:185]
	s_add_i32 m0, s24, 0xc000
	ds_read_b128 v[164:167], v214
	ds_read_b128 v[168:171], v214 offset:1024
	ds_read_b128 v[172:175], v214 offset:2048
	ds_read_b128 v[176:179], v214 offset:3072
	ds_read_b128 v[188:191], v214 offset:4096
	ds_read_b128 v[206:209], v214 offset:5120
	ds_read_b128 v[216:219], v214 offset:6144
	ds_read_b128 v[220:223], v214 offset:7168
	global_load_lds_dwordx4 v[198:199], off
	v_lshl_add_u64 v[198:199], s[50:51], 0, v[186:187]
	s_add_i32 m0, s24, 0xe000
	s_nop 0
	global_load_lds_dwordx4 v[198:199], off
	s_add_i32 vcc_lo, s79, 2
	s_lshl_b32 vcc_lo, vcc_lo, 18
	s_lshl_b32 vcc_hi, s13, 21
	s_add_i32 vcc_lo, vcc_lo, vcc_hi
	s_lshl_b32 vcc_hi, s23, 6
	s_add_i32 vcc_lo, vcc_lo, vcc_hi
	s_lshl_b32 vcc_hi, s12, 10
	s_add_i32 vcc_lo, vcc_lo, vcc_hi
	s_add_u32 vcc_lo, s82, vcc_lo
	s_addc_u32 vcc_hi, s83, 0
	s_mov_b32 m0, 0x22c00
	s_nop 0
	global_load_lds_dwordx4 v224, vcc
	s_add_u32 vcc_lo, vcc_lo, 0x2000
	s_addc_u32 vcc_hi, vcc_hi, 0
	s_mov_b32 m0, 0x22c00
	s_nop 0
	global_load_lds_dwordx4 v224, vcc
	s_add_u32 vcc_lo, vcc_lo, 0x2000
	s_addc_u32 vcc_hi, vcc_hi, 0
	s_mov_b32 m0, 0x22c00
	s_nop 0
	global_load_lds_dwordx4 v224, vcc
	s_add_u32 vcc_lo, vcc_lo, 0x2000
	s_addc_u32 vcc_hi, vcc_hi, 0
	s_mov_b32 m0, 0x22c00
	s_nop 0
	global_load_lds_dwordx4 v224, vcc
	s_waitcnt vmcnt(12)
	s_waitcnt lgkmcnt(0)
	s_barrier
; #define PG8_STAGE(bufoff, gbase, voff) do { _Pragma("unroll") for (int _i = 0; _i < 2; ++_i) \
;         __builtin_amdgcn_global_load_lds((const unsigned*)((const char*)(gbase) + (voff)[_i]), (LAS unsigned*)(lds + (bufoff) + ldsw + _i * 8192), 16, 0, 0); } while (0)
; #define PG8_LDA(dst, b, h) do { _Pragma("unroll") for (int m = 0; m < 4; ++m) _Pragma("unroll") for (int k = 0; k < 2; ++k) dst[m][k] = *(const LAS bf16x8*)(lds + PG8_SA(b, h) + aoff + m * 2048 + k * 1024); } while (0)
; #define PG8_MMA(ai, bj, At, Bt) do { __builtin_amdgcn_s_setprio(1); _Pragma("unroll") for (int m = 0; m < 4; ++m) _Pragma("unroll") for (int n = 0; n < 2; ++n) _Pragma("unroll") for (int k = 0; k < 2; ++k) \
;         acc[ai][bj][m][n] = __builtin_amdgcn_mfma_f32_16x16x32_bf16(Bt[n][k], At[m][k], acc[ai][bj][m][n], 0, 0, 0); __builtin_amdgcn_s_setprio(0); } while (0)
; #define PG8_WAIT_V(n) asm volatile("s_waitcnt vmcnt(" #n ")" ::: "memory")
; #define PG8_WAIT_L(n) asm volatile("s_waitcnt lgkmcnt(" #n ")" ::: "memory")
; #define PG8_BAR __builtin_amdgcn_s_barrier()
; #define PG8_SCHED __builtin_amdgcn_sched_barrier(0)
; template <class Epi, bool ALIGN_EPI>
; __device__ __forceinline__ void gemm_phase(LAS unsigned char* lds, const Gemm g, int G, int cid, const Epi& E) {
;     ...
;             PG8_WAIT_V(8); PG8_WAIT_L(0); PG8_BAR; PG8_MMA(0, 0, At, B0); PG8_MMA(0, 1, At, B1); PG8_BAR; PG8_SCHED;
;             PG8_LDA(At, 0, 1); PG8_STAGE(PG8_SB(0, 0), b2, voffB); PG8_STAGE(PG8_SB(0, 1), b2 + hB, voffB); PG8_STAGE(PG8_SA(0, 0), a2, voffA);
;             PG8_WAIT_V(8); PG8_WAIT_L(0); PG8_BAR; PG8_MMA(1, 0, At, B0); PG8_MMA(1, 1, At, B1); PG8_BAR; PG8_SCHED;
	s_setprio 1
	s_waitcnt lgkmcnt(0)
	v_mfma_f32_16x16x32_bf16 v[160:163], v[68:71], v[164:167], v[160:163]
	v_mfma_f32_16x16x32_bf16 v[156:159], v[80:83], v[164:167], v[156:159]
	v_mfma_f32_16x16x32_bf16 v[144:147], v[68:71], v[172:175], v[144:147]
	v_mfma_f32_16x16x32_bf16 v[140:143], v[80:83], v[172:175], v[140:143]
	v_mfma_f32_16x16x32_bf16 v[124:127], v[68:71], v[188:191], v[124:127]
	v_mfma_f32_16x16x32_bf16 v[120:123], v[80:83], v[188:191], v[120:123]
	v_mfma_f32_16x16x32_bf16 v[108:111], v[68:71], v[216:219], v[108:111]
	v_mfma_f32_16x16x32_bf16 v[104:107], v[80:83], v[216:219], v[104:107]
	v_mfma_f32_16x16x32_bf16 v[160:163], v[76:79], v[168:171], v[160:163]
	v_mfma_f32_16x16x32_bf16 v[156:159], v[84:87], v[168:171], v[156:159]
	v_mfma_f32_16x16x32_bf16 v[144:147], v[76:79], v[176:179], v[144:147]
	v_mfma_f32_16x16x32_bf16 v[140:143], v[84:87], v[176:179], v[140:143]
	v_mfma_f32_16x16x32_bf16 v[124:127], v[76:79], v[206:209], v[124:127]
	v_mfma_f32_16x16x32_bf16 v[120:123], v[84:87], v[206:209], v[120:123]
	v_mfma_f32_16x16x32_bf16 v[108:111], v[76:79], v[220:223], v[108:111]
	v_mfma_f32_16x16x32_bf16 v[104:107], v[84:87], v[220:223], v[104:107]
	s_setprio 0
	s_setprio 1
	v_mfma_f32_16x16x32_bf16 v[152:155], v[88:91], v[164:167], v[152:155]
	v_mfma_f32_16x16x32_bf16 v[148:151], v[96:99], v[164:167], v[148:151]
	v_mfma_f32_16x16x32_bf16 v[132:135], v[88:91], v[172:175], v[132:135]
	v_mfma_f32_16x16x32_bf16 v[128:131], v[96:99], v[172:175], v[128:131]
	v_mfma_f32_16x16x32_bf16 v[116:119], v[88:91], v[188:191], v[116:119]
	v_mfma_f32_16x16x32_bf16 v[112:115], v[96:99], v[188:191], v[112:115]
	v_mfma_f32_16x16x32_bf16 v[72:75], v[88:91], v[216:219], v[72:75]
	v_mfma_f32_16x16x32_bf16 v[64:67], v[96:99], v[216:219], v[64:67]
	v_mfma_f32_16x16x32_bf16 v[152:155], v[92:95], v[168:171], v[152:155]
	v_mfma_f32_16x16x32_bf16 v[148:151], v[100:103], v[168:171], v[148:151]
	v_mfma_f32_16x16x32_bf16 v[132:135], v[92:95], v[176:179], v[132:135]
	v_mfma_f32_16x16x32_bf16 v[128:131], v[100:103], v[176:179], v[128:131]
	v_mfma_f32_16x16x32_bf16 v[116:119], v[92:95], v[206:209], v[116:119]
	v_mfma_f32_16x16x32_bf16 v[112:115], v[100:103], v[206:209], v[112:115]
	v_mfma_f32_16x16x32_bf16 v[72:75], v[92:95], v[220:223], v[72:75]
	v_mfma_f32_16x16x32_bf16 v[64:67], v[100:103], v[220:223], v[64:67]
	s_setprio 0
	s_barrier
	s_add_i32 s6, s6, s23
	v_lshl_add_u64 v[198:199], s[52:53], 0, v[138:139]
	s_mov_b32 m0, s6
	ds_read_b128 v[164:167], v214 offset:16384
	ds_read_b128 v[168:171], v214 offset:17408
	ds_read_b128 v[172:175], v214 offset:18432
	ds_read_b128 v[176:179], v214 offset:19456
	ds_read_b128 v[188:191], v214 offset:20480
	ds_read_b128 v[206:209], v214 offset:21504
	ds_read_b128 v[216:219], v214 offset:22528
	ds_read_b128 v[220:223], v214 offset:23552
	global_load_lds_dwordx4 v[198:199], off
	s_add_i32 m0, s6, 0x2000
	s_add_u32 s6, s52, 0x2000
	v_lshl_add_u64 v[198:199], s[52:53], 0, v[136:137]
	s_addc_u32 s7, s53, 0
	s_add_i32 s50, s86, s23
	global_load_lds_dwordx4 v[198:199], off
	v_lshl_add_u64 v[198:199], s[6:7], 0, v[138:139]
	s_mov_b32 m0, s50
	v_lshl_add_u64 v[200:201], s[54:55], 0, v[180:181]
	global_load_lds_dwordx4 v[198:199], off
	v_lshl_add_u64 v[198:199], s[6:7], 0, v[136:137]
	s_add_i32 m0, s50, 0x2000
	s_nop 0
	global_load_lds_dwordx4 v[198:199], off
	v_lshl_add_u64 v[198:199], s[54:55], 0, v[182:183]
	s_mov_b32 m0, s24
	s_nop 0
	global_load_lds_dwordx4 v[198:199], off
	s_mov_b32 m0, s25
	s_nop 0
	global_load_lds_dwordx4 v[200:201], off
	s_waitcnt vmcnt(12)
	s_waitcnt lgkmcnt(0)
	s_barrier
	s_setprio 1
	s_waitcnt lgkmcnt(0)
	v_mfma_f32_16x16x32_bf16 v[60:63], v[68:71], v[164:167], v[60:63]
	v_mfma_f32_16x16x32_bf16 v[56:59], v[80:83], v[164:167], v[56:59]
	v_mfma_f32_16x16x32_bf16 v[44:47], v[68:71], v[172:175], v[44:47]
	v_mfma_f32_16x16x32_bf16 v[40:43], v[80:83], v[172:175], v[40:43]
	v_mfma_f32_16x16x32_bf16 v[28:31], v[68:71], v[188:191], v[28:31]
	v_mfma_f32_16x16x32_bf16 v[24:27], v[80:83], v[188:191], v[24:27]
	v_mfma_f32_16x16x32_bf16 v[12:15], v[68:71], v[216:219], v[12:15]
	v_mfma_f32_16x16x32_bf16 v[8:11], v[80:83], v[216:219], v[8:11]
	v_mfma_f32_16x16x32_bf16 v[60:63], v[76:79], v[168:171], v[60:63]
	v_mfma_f32_16x16x32_bf16 v[56:59], v[84:87], v[168:171], v[56:59]
	v_mfma_f32_16x16x32_bf16 v[44:47], v[76:79], v[176:179], v[44:47]
	v_mfma_f32_16x16x32_bf16 v[40:43], v[84:87], v[176:179], v[40:43]
	v_mfma_f32_16x16x32_bf16 v[28:31], v[76:79], v[206:209], v[28:31]
	v_mfma_f32_16x16x32_bf16 v[24:27], v[84:87], v[206:209], v[24:27]
	v_mfma_f32_16x16x32_bf16 v[12:15], v[76:79], v[220:223], v[12:15]
	v_mfma_f32_16x16x32_bf16 v[8:11], v[84:87], v[220:223], v[8:11]
	s_setprio 0
	s_setprio 1
	v_mfma_f32_16x16x32_bf16 v[52:55], v[88:91], v[164:167], v[52:55]
	v_mfma_f32_16x16x32_bf16 v[48:51], v[96:99], v[164:167], v[48:51]
	v_mfma_f32_16x16x32_bf16 v[36:39], v[88:91], v[172:175], v[36:39]
	v_mfma_f32_16x16x32_bf16 v[32:35], v[96:99], v[172:175], v[32:35]
	v_mfma_f32_16x16x32_bf16 v[20:23], v[88:91], v[188:191], v[20:23]
	v_mfma_f32_16x16x32_bf16 v[16:19], v[96:99], v[188:191], v[16:19]
	v_mfma_f32_16x16x32_bf16 v[4:7], v[88:91], v[216:219], v[4:7]
	v_mfma_f32_16x16x32_bf16 v[0:3], v[96:99], v[216:219], v[0:3]
	v_mfma_f32_16x16x32_bf16 v[52:55], v[92:95], v[168:171], v[52:55]
	v_mfma_f32_16x16x32_bf16 v[48:51], v[100:103], v[168:171], v[48:51]
	v_mfma_f32_16x16x32_bf16 v[36:39], v[92:95], v[176:179], v[36:39]
	v_mfma_f32_16x16x32_bf16 v[32:35], v[100:103], v[176:179], v[32:35]
	v_mfma_f32_16x16x32_bf16 v[20:23], v[92:95], v[206:209], v[20:23]
	v_mfma_f32_16x16x32_bf16 v[16:19], v[100:103], v[206:209], v[16:19]
	v_mfma_f32_16x16x32_bf16 v[4:7], v[92:95], v[220:223], v[4:7]
	v_mfma_f32_16x16x32_bf16 v[0:3], v[100:103], v[220:223], v[0:3]
	s_setprio 0
	s_barrier
; #define PG8_STAGE(bufoff, gbase, voff) do { _Pragma("unroll") for (int _i = 0; _i < 2; ++_i) \
;         __builtin_amdgcn_global_load_lds((const unsigned*)((const char*)(gbase) + (voff)[_i]), (LAS unsigned*)(lds + (bufoff) + ldsw + _i * 8192), 16, 0, 0); } while (0)
; #define PG8_LDA(dst, b, h) do { _Pragma("unroll") for (int m = 0; m < 4; ++m) _Pragma("unroll") for (int k = 0; k < 2; ++k) dst[m][k] = *(const LAS bf16x8*)(lds + PG8_SA(b, h) + aoff + m * 2048 + k * 1024); } while (0)
; #define PG8_LDB(dst, b, h) do { _Pragma("unroll") for (int n = 0; n < 2; ++n) _Pragma("unroll") for (int k = 0; k < 2; ++k) dst[n][k] = *(const LAS bf16x8*)(lds + PG8_SB(b, h) + boff + n * 2048 + k * 1024); } while (0)
; #define PG8_MMA(ai, bj, At, Bt) do { __builtin_amdgcn_s_setprio(1); _Pragma("unroll") for (int m = 0; m < 4; ++m) _Pragma("unroll") for (int n = 0; n < 2; ++n) _Pragma("unroll") for (int k = 0; k < 2; ++k) \
;         acc[ai][bj][m][n] = __builtin_amdgcn_mfma_f32_16x16x32_bf16(Bt[n][k], At[m][k], acc[ai][bj][m][n], 0, 0, 0); __builtin_amdgcn_s_setprio(0); } while (0)
; #define PG8_WAIT_V(n) asm volatile("s_waitcnt vmcnt(" #n ")" ::: "memory")
; #define PG8_WAIT_L(n) asm volatile("s_waitcnt lgkmcnt(" #n ")" ::: "memory")
; #define PG8_BAR __builtin_amdgcn_s_barrier()
; #define PG8_SCHED __builtin_amdgcn_sched_barrier(0)
; template <class Epi, bool ALIGN_EPI>
; __device__ __forceinline__ void gemm_phase(LAS unsigned char* lds, const Gemm g, int G, int cid, const Epi& E) {
;     ...
;             PG8_WAIT_V(8); PG8_WAIT_L(0); PG8_BAR; PG8_MMA(1, 0, At, B0); PG8_MMA(1, 1, At, B1); PG8_BAR; PG8_SCHED;
;             PG8_LDB(B0, 1, 0); PG8_LDB(B1, 1, 1); PG8_SCHED; PG8_LDA(At, 1, 0); PG8_STAGE(PG8_SA(0, 1), a2 + hA, voffA);
;             PG8_WAIT_V(8); PG8_WAIT_L(0); PG8_BAR; PG8_MMA(0, 0, At, B0); PG8_MMA(0, 1, At, B1); PG8_BAR; PG8_SCHED;
;             PG8_LDA(At, 1, 1); PG8_STAGE(PG8_SB(1, 0), b3, voffB); PG8_STAGE(PG8_SB(1, 1), b3 + hB, voffB); PG8_STAGE(PG8_SA(1, 0), a3, voffA);
	s_add_i32 s50, 0, 0x18000
	s_add_i32 s51, 0, 0x1c000
	v_add_u32_e32 v84, s50, v212
	v_add_u32_e32 v100, s51, v212
	ds_read_b128 v[68:71], v84
	ds_read_b128 v[76:79], v84 offset:1024
	ds_read_b128 v[80:83], v84 offset:2048
	ds_read_b128 v[84:87], v84 offset:3072
	ds_read_b128 v[88:91], v100
	ds_read_b128 v[92:95], v100 offset:1024
	ds_read_b128 v[96:99], v100 offset:2048
	ds_read_b128 v[100:103], v100 offset:3072
	s_add_u32 s6, s54, 0x84000
	s_addc_u32 s7, s55, 0
	s_mov_b32 m0, s56
	v_lshl_add_u64 v[210:211], s[6:7], 0, v[182:183]
	ds_read_b128 v[164:167], v214 offset:32768
	ds_read_b128 v[168:171], v214 offset:33792
	ds_read_b128 v[172:175], v214 offset:34816
	ds_read_b128 v[176:179], v214 offset:35840
	ds_read_b128 v[188:191], v214 offset:36864
	ds_read_b128 v[206:209], v214 offset:37888
	ds_read_b128 v[216:219], v214 offset:38912
	ds_read_b128 v[220:223], v214 offset:39936
	global_load_lds_dwordx4 v[210:211], off
	v_lshl_add_u64 v[210:211], s[6:7], 0, v[180:181]
	s_mov_b32 m0, s57
	s_nop 0
	global_load_lds_dwordx4 v[210:211], off
	s_add_u32 vcc_lo, vcc_lo, 0x2000
	s_addc_u32 vcc_hi, vcc_hi, 0
	s_mov_b32 m0, 0x22c00
	s_nop 0
	global_load_lds_dwordx4 v224, vcc
	s_add_u32 vcc_lo, vcc_lo, 0x2000
	s_addc_u32 vcc_hi, vcc_hi, 0
	s_mov_b32 m0, 0x22c00
	s_nop 0
	global_load_lds_dwordx4 v224, vcc
	s_add_u32 vcc_lo, vcc_lo, 0x2000
	s_addc_u32 vcc_hi, vcc_hi, 0
	s_mov_b32 m0, 0x22c00
	s_nop 0
	global_load_lds_dwordx4 v224, vcc
	s_add_u32 vcc_lo, vcc_lo, 0x2000
	s_addc_u32 vcc_hi, vcc_hi, 0
	s_mov_b32 m0, 0x22c00
	s_nop 0
	global_load_lds_dwordx4 v224, vcc
	s_waitcnt vmcnt(12)
	s_waitcnt lgkmcnt(0)
	s_barrier
	s_setprio 1
	s_waitcnt lgkmcnt(0)
	v_mfma_f32_16x16x32_bf16 v[160:163], v[68:71], v[164:167], v[160:163]
	v_mfma_f32_16x16x32_bf16 v[156:159], v[80:83], v[164:167], v[156:159]
	v_mfma_f32_16x16x32_bf16 v[144:147], v[68:71], v[172:175], v[144:147]
	v_mfma_f32_16x16x32_bf16 v[140:143], v[80:83], v[172:175], v[140:143]
	v_mfma_f32_16x16x32_bf16 v[124:127], v[68:71], v[188:191], v[124:127]
	v_mfma_f32_16x16x32_bf16 v[120:123], v[80:83], v[188:191], v[120:123]
	v_mfma_f32_16x16x32_bf16 v[108:111], v[68:71], v[216:219], v[108:111]
	v_mfma_f32_16x16x32_bf16 v[104:107], v[80:83], v[216:219], v[104:107]
	v_mfma_f32_16x16x32_bf16 v[160:163], v[76:79], v[168:171], v[160:163]
	v_mfma_f32_16x16x32_bf16 v[156:159], v[84:87], v[168:171], v[156:159]
	v_mfma_f32_16x16x32_bf16 v[144:147], v[76:79], v[176:179], v[144:147]
	v_mfma_f32_16x16x32_bf16 v[140:143], v[84:87], v[176:179], v[140:143]
	v_mfma_f32_16x16x32_bf16 v[124:127], v[76:79], v[206:209], v[124:127]
	v_mfma_f32_16x16x32_bf16 v[120:123], v[84:87], v[206:209], v[120:123]
	v_mfma_f32_16x16x32_bf16 v[108:111], v[76:79], v[220:223], v[108:111]
	v_mfma_f32_16x16x32_bf16 v[104:107], v[84:87], v[220:223], v[104:107]
	s_setprio 0
	s_setprio 1
	v_mfma_f32_16x16x32_bf16 v[152:155], v[88:91], v[164:167], v[152:155]
	v_mfma_f32_16x16x32_bf16 v[148:151], v[96:99], v[164:167], v[148:151]
	v_mfma_f32_16x16x32_bf16 v[132:135], v[88:91], v[172:175], v[132:135]
	v_mfma_f32_16x16x32_bf16 v[128:131], v[96:99], v[172:175], v[128:131]
	v_mfma_f32_16x16x32_bf16 v[116:119], v[88:91], v[188:191], v[116:119]
	v_mfma_f32_16x16x32_bf16 v[112:115], v[96:99], v[188:191], v[112:115]
	v_mfma_f32_16x16x32_bf16 v[72:75], v[88:91], v[216:219], v[72:75]
	v_mfma_f32_16x16x32_bf16 v[64:67], v[96:99], v[216:219], v[64:67]
	v_mfma_f32_16x16x32_bf16 v[152:155], v[92:95], v[168:171], v[152:155]
	v_mfma_f32_16x16x32_bf16 v[148:151], v[100:103], v[168:171], v[148:151]
	v_mfma_f32_16x16x32_bf16 v[132:135], v[92:95], v[176:179], v[132:135]
	v_mfma_f32_16x16x32_bf16 v[128:131], v[100:103], v[176:179], v[128:131]
	v_mfma_f32_16x16x32_bf16 v[116:119], v[92:95], v[206:209], v[116:119]
	v_mfma_f32_16x16x32_bf16 v[112:115], v[100:103], v[206:209], v[112:115]
	v_mfma_f32_16x16x32_bf16 v[72:75], v[92:95], v[220:223], v[72:75]
	v_mfma_f32_16x16x32_bf16 v[64:67], v[100:103], v[220:223], v[64:67]
	s_setprio 0
	s_barrier
	s_add_u32 s6, s52, 0x10000
	s_addc_u32 s7, s53, 0
	s_add_i32 s50, s50, s23
	v_lshl_add_u64 v[210:211], s[6:7], 0, v[138:139]
	s_mov_b32 m0, s50
	ds_read_b128 v[164:167], v214 offset:49152
	ds_read_b128 v[168:171], v214 offset:50176
	ds_read_b128 v[172:175], v214 offset:51200
	ds_read_b128 v[176:179], v214 offset:52224
	ds_read_b128 v[188:191], v214 offset:53248
	ds_read_b128 v[206:209], v214 offset:54272
	ds_read_b128 v[216:219], v214 offset:55296
	ds_read_b128 v[220:223], v214 offset:56320
	global_load_lds_dwordx4 v[210:211], off
	s_add_i32 m0, s50, 0x2000
	v_lshl_add_u64 v[210:211], s[6:7], 0, v[136:137]
	s_add_u32 s6, s52, 0x12000
	s_addc_u32 s7, s53, 0
	s_add_i32 s50, s51, s23
	global_load_lds_dwordx4 v[210:211], off
	v_lshl_add_u64 v[210:211], s[6:7], 0, v[138:139]
	s_mov_b32 m0, s50
	v_lshl_add_u64 v[198:199], v[198:199], 0, s[36:37]
	global_load_lds_dwordx4 v[210:211], off
	v_lshl_add_u64 v[210:211], s[6:7], 0, v[136:137]
	s_add_i32 m0, s50, 0x2000
	s_nop 0
	global_load_lds_dwordx4 v[210:211], off
	s_mov_b32 m0, s59
	s_nop 0
	global_load_lds_dwordx4 v[198:199], off
	v_lshl_add_u64 v[198:199], v[200:201], 0, s[36:37]
	s_mov_b32 m0, s72
	s_nop 0
	global_load_lds_dwordx4 v[198:199], off
	s_waitcnt vmcnt(12)
	s_waitcnt lgkmcnt(0)
	s_barrier
; #define PG8_MMA(ai, bj, At, Bt) do { __builtin_amdgcn_s_setprio(1); _Pragma("unroll") for (int m = 0; m < 4; ++m) _Pragma("unroll") for (int n = 0; n < 2; ++n) _Pragma("unroll") for (int k = 0; k < 2; ++k) \
;         acc[ai][bj][m][n] = __builtin_amdgcn_mfma_f32_16x16x32_bf16(Bt[n][k], At[m][k], acc[ai][bj][m][n], 0, 0, 0); __builtin_amdgcn_s_setprio(0); } while (0)
; #define PG8_WAIT_V(n) asm volatile("s_waitcnt vmcnt(" #n ")" ::: "memory")
; #define PG8_WAIT_L(n) asm volatile("s_waitcnt lgkmcnt(" #n ")" ::: "memory")
; #define PG8_BAR __builtin_amdgcn_s_barrier()
; #define PG8_SCHED __builtin_amdgcn_sched_barrier(0)
; template <class Epi, bool ALIGN_EPI>
; __device__ __forceinline__ void gemm_phase(LAS unsigned char* lds, const Gemm g, int G, int cid, const Epi& E) {
;     ...
;         for (int t = 0; t < nt; t += 2) {
;     ...
;             PG8_WAIT_V(8); PG8_WAIT_L(0); PG8_BAR; PG8_MMA(1, 0, At, B0); PG8_MMA(1, 1, At, B1); PG8_BAR; PG8_SCHED;
;         }
	s_setprio 1
	s_waitcnt lgkmcnt(0)
	v_mfma_f32_16x16x32_bf16 v[60:63], v[68:71], v[164:167], v[60:63]
	v_mfma_f32_16x16x32_bf16 v[56:59], v[80:83], v[164:167], v[56:59]
	v_mfma_f32_16x16x32_bf16 v[44:47], v[68:71], v[172:175], v[44:47]
	v_mfma_f32_16x16x32_bf16 v[40:43], v[80:83], v[172:175], v[40:43]
	v_mfma_f32_16x16x32_bf16 v[28:31], v[68:71], v[188:191], v[28:31]
	v_mfma_f32_16x16x32_bf16 v[24:27], v[80:83], v[188:191], v[24:27]
	v_mfma_f32_16x16x32_bf16 v[12:15], v[68:71], v[216:219], v[12:15]
	v_mfma_f32_16x16x32_bf16 v[8:11], v[80:83], v[216:219], v[8:11]
	v_mfma_f32_16x16x32_bf16 v[60:63], v[76:79], v[168:171], v[60:63]
	v_mfma_f32_16x16x32_bf16 v[56:59], v[84:87], v[168:171], v[56:59]
	v_mfma_f32_16x16x32_bf16 v[44:47], v[76:79], v[176:179], v[44:47]
	v_mfma_f32_16x16x32_bf16 v[40:43], v[84:87], v[176:179], v[40:43]
	v_mfma_f32_16x16x32_bf16 v[28:31], v[76:79], v[206:209], v[28:31]
	v_mfma_f32_16x16x32_bf16 v[24:27], v[84:87], v[206:209], v[24:27]
	v_mfma_f32_16x16x32_bf16 v[12:15], v[76:79], v[220:223], v[12:15]
	v_mfma_f32_16x16x32_bf16 v[8:11], v[84:87], v[220:223], v[8:11]
	s_setprio 0
	s_setprio 1
	v_mfma_f32_16x16x32_bf16 v[52:55], v[88:91], v[164:167], v[52:55]
	v_mfma_f32_16x16x32_bf16 v[48:51], v[96:99], v[164:167], v[48:51]
	v_mfma_f32_16x16x32_bf16 v[36:39], v[88:91], v[172:175], v[36:39]
	v_mfma_f32_16x16x32_bf16 v[32:35], v[96:99], v[172:175], v[32:35]
	v_mfma_f32_16x16x32_bf16 v[20:23], v[88:91], v[188:191], v[20:23]
	v_mfma_f32_16x16x32_bf16 v[16:19], v[96:99], v[188:191], v[16:19]
	v_mfma_f32_16x16x32_bf16 v[4:7], v[88:91], v[216:219], v[4:7]
	v_mfma_f32_16x16x32_bf16 v[0:3], v[96:99], v[216:219], v[0:3]
	v_mfma_f32_16x16x32_bf16 v[52:55], v[92:95], v[168:171], v[52:55]
	v_mfma_f32_16x16x32_bf16 v[48:51], v[100:103], v[168:171], v[48:51]
	v_mfma_f32_16x16x32_bf16 v[36:39], v[92:95], v[176:179], v[36:39]
	v_mfma_f32_16x16x32_bf16 v[32:35], v[100:103], v[176:179], v[32:35]
	v_mfma_f32_16x16x32_bf16 v[20:23], v[92:95], v[206:209], v[20:23]
	v_mfma_f32_16x16x32_bf16 v[16:19], v[100:103], v[206:209], v[16:19]
	v_mfma_f32_16x16x32_bf16 v[4:7], v[92:95], v[220:223], v[4:7]
	v_mfma_f32_16x16x32_bf16 v[0:3], v[100:103], v[220:223], v[0:3]
	s_setprio 0
	s_barrier
	s_add_i32 s79, s79, 2
	s_add_u32 s77, s77, 0x20000
	s_addc_u32 s78, s78, 0
	s_cmp_lt_u32 s79, 6
	s_mov_b64 s[50:51], s[44:45]
	s_cbranch_scc1 .LBB0_169
; #define LAS __attribute__((address_space(3)))
;     __device__ __forceinline__ void operator()(const f32x4 (&acc)[2][2][4][2], const Unit& u, int wr, int wc, int fr, int fq, const LAS float*) const {
;         const int row0 = u.pm * BM + wr * 64 + fr, col0 = u.pn * BM + wc * 32 + 8 * fq;
;         f32x4 bv[2][2], sv[2][2];
; #pragma unroll
;         for (int bj = 0; bj < 2; ++bj)
; #pragma unroll
;             for (int n = 0; n < 2; ++n) { bv[bj][n] = HB ? *(const f32x4*)(bias + col0 + bj * HALF + 4 * n) : (f32x4){0.f, 0.f, 0.f, 0.f};
;                                            sv[bj][n] = HB ? *(const f32x4*)(scale + col0 + bj * HALF + 4 * n) : (f32x4){1.f, 1.f, 1.f, 1.f}; }
;         constexpr int NB = HB ? 4 : 2, MB = 4 / (NB / 2);
; #pragma unroll
;         for (int am = 0; am < NB; ++am) { const int ai = am / (NB / 2), m0 = (am % (NB / 2)) * MB;
;             f32x4 xo[4][2][2];
; #pragma unroll
;             for (int m = m0; m < m0 + MB; ++m) { const float* xr = Xs + (size_t)(row0 + ai * HALF + m * 16) * DM + col0;
; #pragma unroll
;                 for (int bj = 0; bj < 2; ++bj) { xo[m][bj][0] = *(const f32x4*)(xr + bj * HALF); xo[m][bj][1] = *(const f32x4*)(xr + bj * HALF + 4); } }
; #pragma unroll
;             for (int m = m0; m < m0 + MB; ++m) { const int row = row0 + ai * HALF + m * 16; float ss = 0.f;
;                 float* xr = X + (size_t)row * DM + col0; bf16_t* xb = XB + (size_t)row * ALD + col0;
; #pragma unroll
;                 for (int bj = 0; bj < 2; ++bj) { f32x4 x0 = xo[m][bj][0], x1 = xo[m][bj][1];
;                     if (HB) { x0 += (acc[ai][bj][m][0] + bv[bj][0]) * sv[bj][0]; x1 += (acc[ai][bj][m][1] + bv[bj][1]) * sv[bj][1]; } else { x0 += acc[ai][bj][m][0]; x1 += acc[ai][bj][m][1]; }
;                     *(f32x4*)(xr + bj * HALF) = x0; *(f32x4*)(xr + bj * HALF + 4) = x1;
;                     ss += (x0[0] * x0[0] + x0[1] * x0[1]) + (x0[2] * x0[2] + x0[3] * x0[3]) + (x1[0] * x1[0] + x1[1] * x1[1]) + (x1[2] * x1[2] + x1[3] * x1[3]);
;                     u32x4 w; w.x = cvt_pk_bf16(x0[0], x0[1]); w.y = cvt_pk_bf16(x0[2], x0[3]); w.z = cvt_pk_bf16(x1[0], x1[1]); w.w = cvt_pk_bf16(x1[2], x1[3]);
;                     if (feeds) *(u32x4*)(xb + bj * HALF) = w; }
;                 ss += __shfl_xor(ss, 16); ss += __shfl_xor(ss, 32);
;                 if (fq == 0 && feeds) part[(size_t)row * NPART + u.pn * 4 + wc] = ss; }
	v_lshl_or_b32 v188, s12, 8, v213
	v_ashrrev_i32_e32 v189, 31, v188
	v_lshl_add_u32 v190, s13, 8, v197
	v_lshlrev_b64 v[198:199], 2, v[188:189]
	v_ashrrev_i32_e32 v191, 31, v190
	v_lshl_add_u64 v[206:207], s[82:83], 0, v[198:199]
	v_lshlrev_b64 v[200:201], 13, v[190:191]
	v_lshl_add_u64 v[68:69], s[28:29], 0, v[198:199]
	v_lshl_add_u64 v[80:81], s[46:47], 0, v[198:199]
	v_lshl_add_u64 v[164:165], v[206:207], 0, v[200:201]
	global_load_dwordx4 v[92:95], v[68:69], off offset:16
	global_load_dwordx4 v[100:103], v[68:69], off
	global_load_dwordx4 v[88:91], v[80:81], off offset:16
	global_load_dwordx4 v[96:99], v[80:81], off
	global_load_dwordx4 v[76:79], v[68:69], off offset:528
	global_load_dwordx4 v[84:87], v[68:69], off offset:512
	s_nop 0
	global_load_dwordx4 v[68:71], v[80:81], off offset:528
	s_nop 0
	global_load_dwordx4 v[80:83], v[80:81], off offset:512
	s_nop 0
	global_load_dwordx4 v[216:219], v[164:165], off offset:16
	global_load_dwordx4 v[220:223], v[164:165], off
	global_load_dwordx4 v[224:227], v[164:165], off offset:528
	global_load_dwordx4 v[228:231], v[164:165], off offset:512
	v_or_b32_e32 v208, 16, v190
	v_ashrrev_i32_e32 v209, 31, v208
	v_lshlrev_b64 v[210:211], 13, v[208:209]
	v_lshl_add_u64 v[168:169], v[206:207], 0, v[210:211]
	global_load_dwordx4 v[172:175], v[168:169], off offset:16
	global_load_dwordx4 v[176:179], v[168:169], off
	global_load_dwordx4 v[164:167], v[168:169], off offset:528
	s_nop 0
	global_load_dwordx4 v[168:171], v[168:169], off offset:512
	v_lshl_add_u64 v[200:201], s[82:83], 0, v[200:201]
	v_lshl_add_u64 v[198:199], v[200:201], 0, v[198:199]
	v_mov_b64_e32 v[200:201], s[4:5]
	v_mad_i64_i32 v[200:201], s[6:7], v190, s66, v[200:201]
	v_lshl_add_u64 v[200:201], v[188:189], 1, v[200:201]
	s_lshl_b32 s44, s12, 2
	s_ashr_i32 s45, s44, 31
	s_waitcnt vmcnt(0)
	v_pk_add_f32 v[156:157], v[156:157], v[92:93]
	v_pk_add_f32 v[162:163], v[162:163], v[102:103]
	v_pk_add_f32 v[160:161], v[160:161], v[100:101]
	v_pk_add_f32 v[158:159], v[158:159], v[94:95]
	v_pk_add_f32 v[148:149], v[148:149], v[76:77]
	v_pk_fma_f32 v[156:157], v[88:89], v[156:157], v[216:217]
	v_pk_fma_f32 v[162:163], v[98:99], v[162:163], v[222:223]
	v_pk_fma_f32 v[160:161], v[96:97], v[160:161], v[220:221]
	v_mul_f32_e32 v216, v163, v163
	v_mul_f32_e32 v215, v161, v161
	v_fmac_f32_e32 v215, v160, v160
	v_fmac_f32_e32 v216, v162, v162
	v_pk_add_f32 v[154:155], v[154:155], v[86:87]
	v_pk_add_f32 v[152:153], v[152:153], v[84:85]
	v_add_f32_e32 v215, v215, v216
	v_mul_f32_e32 v216, v157, v157
	v_pk_fma_f32 v[154:155], v[82:83], v[154:155], v[230:231]
	v_pk_fma_f32 v[152:153], v[80:81], v[152:153], v[228:229]
	v_pk_fma_f32 v[158:159], v[90:91], v[158:159], v[218:219]
	global_store_dwordx4 v[198:199], v[160:163], off
	global_store_dwordx4 v[198:199], v[156:159], off offset:16
	v_fmac_f32_e32 v216, v156, v156
	v_cvt_pk_bf16_f32 v160, v160, v161
	v_cvt_pk_bf16_f32 v161, v162, v163
	v_cvt_pk_bf16_f32 v162, v156, v157
	v_pk_fma_f32 v[148:149], v[68:69], v[148:149], v[224:225]
	v_mul_f32_e32 v156, v153, v153
	v_mul_f32_e32 v157, v155, v155
	v_fmac_f32_e32 v156, v152, v152
	v_fmac_f32_e32 v157, v154, v154
	v_pk_add_f32 v[150:151], v[150:151], v[78:79]
	v_add_f32_e32 v156, v156, v157
	v_mul_f32_e32 v157, v149, v149
	v_cvt_pk_bf16_f32 v163, v158, v159
	global_store_dwordx4 v[200:201], v[160:163], off
	v_pk_fma_f32 v[150:151], v[70:71], v[150:151], v[226:227]
	global_store_dwordx4 v[198:199], v[152:155], off offset:512
	global_store_dwordx4 v[198:199], v[148:151], off offset:528
	v_fmac_f32_e32 v157, v148, v148
	v_cvt_pk_bf16_f32 v152, v152, v153
	v_cvt_pk_bf16_f32 v153, v154, v155
	v_cvt_pk_bf16_f32 v154, v148, v149
	v_add_f32_e32 v215, v215, v216
	v_and_b32_e32 v149, 64, v239
	v_mul_f32_e32 v216, v159, v159
	v_add_f32_e32 v156, v156, v157
	v_mul_f32_e32 v157, v151, v151
	v_xor_b32_e32 v148, 16, v239
	v_add_u32_e32 v149, 64, v149
	v_fmac_f32_e32 v216, v158, v158
	v_fmac_f32_e32 v157, v150, v150
	v_cmp_lt_i32_e32 vcc, v148, v149
	v_add_f32_e32 v215, v216, v215
	v_add_f32_e32 v156, v157, v156
	v_cndmask_b32_e32 v148, v239, v148, vcc
	v_add_f32_e32 v156, v215, v156
	v_cvt_pk_bf16_f32 v155, v150, v151
	global_store_dwordx4 v[200:201], v[152:155], off offset:256
	v_xor_b32_e32 v150, 32, v239
	v_cmp_lt_i32_e32 vcc, v150, v149
	v_lshlrev_b32_e32 v154, 2, v148
	ds_bpermute_b32 v148, v154, v156
	v_cndmask_b32_e32 v149, v239, v150, vcc
	v_lshlrev_b32_e32 v155, 2, v149
	s_waitcnt lgkmcnt(0)
	v_add_f32_e32 v148, v156, v148
	ds_bpermute_b32 v149, v155, v148
	s_and_saveexec_b64 s[50:51], s[38:39]
	s_cbranch_execz .LBB0_172
	v_lshlrev_b64 v[150:151], 7, v[190:191]
	v_lshl_add_u64 v[150:151], s[94:95], 0, v[150:151]
	v_lshl_add_u64 v[150:151], s[44:45], 2, v[150:151]
	s_lshl_b32 s30, s58, 2
	v_lshl_add_u64 v[150:151], v[150:151], 0, s[30:31]
	s_waitcnt lgkmcnt(0)
	v_add_f32_e32 v148, v148, v149
	global_store_dword v[150:151], v148, off
